# NA: rpb bias-table load hoisted next to Q loads (removes a serialized memory round trip per unit)
# speedup vs baseline: 1.0755x; 1.0038x over previous
.LBB0_1385:
	s_ashr_i32 s0, s28, 7
	s_lshl_b32 s1, s28, 1
	s_bfe_u32 s7, s28, 0x30004
	s_and_b32 s6, s1, 30
	s_lshl_b32 s1, s0, 8
	v_mov_b32_e32 v2, v162
	s_add_i32 s1, s1, 0x8000
	s_lshl_b32 s8, s7, 7
	s_add_u32 s4, s31, s8
	v_lshlrev_b32_e32 v0, 4, v2
	s_addc_u32 s5, s33, 0
	v_and_b32_e32 v0, 0x70, v0
	v_ashrrev_i32_e32 v3, 3, v2
	v_lshl_add_u64 v[16:17], s[4:5], 0, v[0:1]
	s_add_u32 s4, s29, s8
	v_add_u32_e32 v4, s1, v3
	s_addc_u32 s5, s30, 0
	v_ashrrev_i32_e32 v5, 31, v4
	v_lshl_add_u64 v[20:21], s[4:5], 0, v[0:1]
	v_lshlrev_b64 v[4:5], 10, v[4:5]
	v_lshl_add_u64 v[6:7], v[16:17], 0, v[4:5]
	v_lshl_add_u64 v[4:5], v[20:21], 0, v[4:5]
	v_add_u32_e32 v28, 0x200, v2
	global_load_dwordx4 v[8:11], v[6:7], off
	global_load_dwordx4 v[12:15], v[4:5], off
	v_ashrrev_i32_e32 v4, 3, v28
	v_add_u32_e32 v6, s1, v4
	v_ashrrev_i32_e32 v7, 31, v6
	v_lshlrev_b64 v[6:7], 10, v[6:7]
	v_add_u32_e32 v32, 0x400, v2
	v_lshl_add_u64 v[22:23], v[16:17], 0, v[6:7]
	v_lshl_add_u64 v[6:7], v[20:21], 0, v[6:7]
	v_ashrrev_i32_e32 v5, 3, v32
	global_load_dwordx4 v[58:61], v[22:23], off
	global_load_dwordx4 v[62:65], v[6:7], off
	v_add_u32_e32 v6, s1, v5
	v_ashrrev_i32_e32 v7, 31, v6
	v_lshlrev_b64 v[6:7], 10, v[6:7]
	v_lshl_add_u64 v[22:23], v[16:17], 0, v[6:7]
	v_lshl_add_u64 v[6:7], v[20:21], 0, v[6:7]
	v_add_u32_e32 v33, 0x600, v2
	global_load_dwordx4 v[66:69], v[22:23], off
	global_load_dwordx4 v[70:73], v[6:7], off
	v_ashrrev_i32_e32 v6, 3, v33
	v_add_u32_e32 v22, s1, v6
	v_ashrrev_i32_e32 v23, 31, v22
	v_sub_u32_e64 v19, s6, 4 clamp
	v_lshlrev_b64 v[22:23], 10, v[22:23]
	s_ashr_i32 s1, s0, 31
	v_lshl_add_u64 v[24:25], v[16:17], 0, v[22:23]
	v_lshl_add_u64 v[22:23], v[20:21], 0, v[22:23]
	v_min_u32_e32 v7, 24, v19
	v_lshrrev_b32_e32 v19, 3, v2
	s_lshl_b64 s[0:1], s[0:1], 11
	global_load_dwordx4 v[74:77], v[24:25], off
	global_load_dwordx4 v[78:81], v[22:23], off
	v_and_or_b32 v22, v19, 63, s0
	v_ashrrev_i32_e32 v19, 9, v2
	v_add_lshl_u32 v24, v19, v7, 6
	v_ashrrev_i32_e32 v19, 9, v28
	v_mov_b32_e32 v23, s1
	v_ashrrev_i32_e32 v25, 31, v24
	v_add_lshl_u32 v28, v19, v7, 6
	v_lshl_add_u64 v[24:25], v[22:23], 0, v[24:25]
	v_ashrrev_i32_e32 v29, 31, v28
	v_lshlrev_b64 v[24:25], 10, v[24:25]
	v_lshl_add_u64 v[28:29], v[22:23], 0, v[28:29]
	v_lshl_add_u64 v[26:27], v[16:17], 0, v[24:25]
	v_lshlrev_b64 v[28:29], 10, v[28:29]
	v_ashrrev_i32_e32 v19, 9, v32
	v_lshl_add_u64 v[30:31], v[16:17], 0, v[28:29]
	global_load_dwordx4 v[82:85], v[26:27], off
	global_load_dwordx4 v[86:89], v[30:31], off
	v_add_lshl_u32 v26, v19, v7, 6
	v_ashrrev_i32_e32 v19, 9, v33
	v_ashrrev_i32_e32 v27, 31, v26
	v_add_lshl_u32 v32, v19, v7, 6
	v_lshl_add_u64 v[26:27], v[22:23], 0, v[26:27]
	v_ashrrev_i32_e32 v33, 31, v32
	v_lshlrev_b64 v[26:27], 10, v[26:27]
	v_lshl_add_u64 v[32:33], v[22:23], 0, v[32:33]
	v_lshl_add_u64 v[30:31], v[16:17], 0, v[26:27]
	v_lshlrev_b64 v[34:35], 10, v[32:33]
	v_add_u32_e32 v19, 0x800, v2
	v_lshl_add_u64 v[32:33], v[16:17], 0, v[34:35]
	global_load_dwordx4 v[90:93], v[30:31], off
	global_load_dwordx4 v[94:97], v[32:33], off
	v_ashrrev_i32_e32 v30, 9, v19
	v_add_u32_e32 v118, 0xa00, v2
	v_add_lshl_u32 v30, v30, v7, 6
	v_ashrrev_i32_e32 v32, 9, v118
	v_ashrrev_i32_e32 v31, 31, v30
	v_add_lshl_u32 v32, v32, v7, 6
	v_lshl_add_u64 v[30:31], v[22:23], 0, v[30:31]
	v_ashrrev_i32_e32 v33, 31, v32
	v_lshlrev_b64 v[36:37], 10, v[30:31]
	v_lshl_add_u64 v[32:33], v[22:23], 0, v[32:33]
	v_lshl_add_u64 v[30:31], v[16:17], 0, v[36:37]
	v_lshlrev_b64 v[42:43], 10, v[32:33]
	v_add_u32_e32 v119, 0xc00, v2
	v_lshl_add_u64 v[32:33], v[16:17], 0, v[42:43]
	global_load_dwordx4 v[98:101], v[30:31], off
	global_load_dwordx4 v[102:105], v[32:33], off
	v_ashrrev_i32_e32 v30, 9, v119
	v_add_u32_e32 v120, 0xe00, v2
	v_add_lshl_u32 v30, v30, v7, 6
	v_ashrrev_i32_e32 v32, 9, v120
	v_ashrrev_i32_e32 v31, 31, v30
	v_add_lshl_u32 v32, v32, v7, 6
	v_lshl_add_u64 v[30:31], v[22:23], 0, v[30:31]
	v_ashrrev_i32_e32 v33, 31, v32
	v_lshlrev_b64 v[44:45], 10, v[30:31]
	v_lshl_add_u64 v[32:33], v[22:23], 0, v[32:33]
	v_lshl_add_u64 v[30:31], v[16:17], 0, v[44:45]
	v_lshlrev_b64 v[50:51], 10, v[32:33]
	v_add_u32_e32 v122, 0x1000, v2
	v_lshl_add_u64 v[32:33], v[16:17], 0, v[50:51]
	global_load_dwordx4 v[106:109], v[30:31], off
	global_load_dwordx4 v[110:113], v[32:33], off
	v_ashrrev_i32_e32 v30, 9, v122
	v_add_lshl_u32 v30, v30, v7, 6
	v_ashrrev_i32_e32 v31, 31, v30
	v_lshl_add_u64 v[22:23], v[22:23], 0, v[30:31]
	v_lshlrev_b64 v[52:53], 10, v[22:23]
	v_lshl_add_u64 v[16:17], v[16:17], 0, v[52:53]
	v_lshl_add_u64 v[22:23], v[20:21], 0, v[24:25]
	global_load_dwordx4 v[114:117], v[16:17], off
	s_nop 0
	global_load_dwordx4 v[22:25], v[22:23], off
	v_lshl_add_u64 v[16:17], v[20:21], 0, v[28:29]
	v_lshl_add_u64 v[30:31], v[20:21], 0, v[26:27]
	global_load_dwordx4 v[26:29], v[16:17], off
	s_nop 0
	global_load_dwordx4 v[30:33], v[30:31], off
	v_lshl_add_u64 v[16:17], v[20:21], 0, v[34:35]
	v_lshl_add_u64 v[38:39], v[20:21], 0, v[36:37]
	global_load_dwordx4 v[34:37], v[16:17], off
	s_nop 0
	global_load_dwordx4 v[38:41], v[38:39], off
	v_lshl_add_u64 v[16:17], v[20:21], 0, v[42:43]
	v_lshl_add_u64 v[46:47], v[20:21], 0, v[44:45]
	global_load_dwordx4 v[42:45], v[16:17], off
	s_nop 0
	global_load_dwordx4 v[46:49], v[46:47], off
	v_lshl_add_u64 v[16:17], v[20:21], 0, v[50:51]
	v_lshl_add_u64 v[20:21], v[20:21], 0, v[52:53]
	global_load_dwordx4 v[50:53], v[16:17], off
	global_load_dwordx4 v[54:57], v[20:21], off
	v_or_b32_e32 v16, 0x14400, v0
	v_mul_lo_u32 v20, v3, s42
	v_or_b32_e32 v17, 0x1d400, v0
	v_add_u32_e32 v21, v16, v20
	s_waitcnt vmcnt(25)
	ds_write_b128 v21, v[8:11]
	v_add_u32_e32 v8, v17, v20
	s_waitcnt vmcnt(24)
	ds_write_b128 v8, v[12:15]
	v_mul_lo_u32 v8, v4, s42
	v_add_u32_e32 v9, v16, v8
	s_waitcnt vmcnt(23)
	ds_write_b128 v9, v[58:61]
	v_add_u32_e32 v9, v17, v8
	s_waitcnt vmcnt(22)
	ds_write_b128 v9, v[62:65]
	v_ashrrev_i32_e32 v211, 8, v2
	v_lshrrev_b32_e32 v210, 2, v2
	v_add_u32_e32 v211, s6, v211
	v_and_b32_e32 v212, 48, v210
	v_lshlrev_b32_e32 v210, 6, v211
	v_and_b32_e32 v213, 15, v2
	v_ashrrev_i32_e32 v211, 31, v210
	v_lshl_add_u64 v[210:211], s[0:1], 0, v[210:211]
	v_or_b32_e32 v212, v212, v213
	v_or_b32_e32 v210, v212, v210
	s_lshl_b32 s98, s7, 7
	s_mov_b32 s99, 0
	v_lshlrev_b64 v[210:211], 10, v[210:211]
	v_bfe_u32 v212, v2, 4, 2
	v_lshl_add_u64 v[210:211], s[64:65], 0, v[210:211]
	v_lshlrev_b32_e32 v212, 4, v212
	v_mov_b32_e32 v213, 0
	v_lshl_add_u64 v[210:211], v[210:211], 0, s[98:99]
	v_lshl_add_u64 v[210:211], v[210:211], 0, v[212:213]
	global_load_dwordx4 v[58:61], v[210:211], off
	global_load_dwordx4 v[62:65], v[210:211], off offset:64
	v_readlane_b32 s100, v247, 33
	v_readlane_b32 s101, v247, 34
	s_mul_i32 s98, s7, 0x1d1
	v_add_u32_e32 v212, s98, v2
	v_min_u32_e32 v212, 0xe87, v212
	v_mov_b32_e32 v213, 0
	v_lshl_add_u64 v[212:213], v[212:213], 2, s[100:101]
	global_load_dword v214, v[212:213], off
	v_mul_lo_u32 v9, v5, s42
	v_add_u32_e32 v10, v16, v9
	s_waitcnt vmcnt(21)
	ds_write_b128 v10, v[66:69]
	v_add_u32_e32 v10, v17, v9
	s_waitcnt vmcnt(20)
	ds_write_b128 v10, v[70:73]
	v_mul_lo_u32 v10, v6, s42
	v_add_u32_e32 v11, v16, v10
	s_waitcnt vmcnt(19)
	ds_write_b128 v11, v[74:77]
	v_add_u32_e32 v11, v17, v10
	s_waitcnt vmcnt(18)
	ds_write_b128 v11, v[78:81]
	v_add_u32_e32 v11, v0, v20
	v_add_u32_e32 v8, v0, v8
	s_waitcnt vmcnt(17)
	ds_write_b128 v11, v[82:85]
	s_waitcnt vmcnt(16)
	ds_write_b128 v8, v[86:89]
	v_add_u32_e32 v8, v0, v9
	v_ashrrev_i32_e32 v12, 3, v19
	s_waitcnt vmcnt(15)
	ds_write_b128 v8, v[90:93]
	v_add_u32_e32 v8, v0, v10
	s_waitcnt vmcnt(14)
	ds_write_b128 v8, v[94:97]
	v_mad_u64_u32 v[8:9], s[4:5], v12, s42, v[0:1]
	v_ashrrev_i32_e32 v11, 3, v118
	v_ashrrev_i32_e32 v10, 3, v119
	v_cmp_gt_i32_e32 vcc, s43, v2
	s_waitcnt vmcnt(13)
	ds_write_b128 v8, v[98:101]
	v_mad_u64_u32 v[8:9], s[4:5], v11, s42, v[0:1]
	s_waitcnt vmcnt(12)
	ds_write_b128 v8, v[102:105]
	v_mad_u64_u32 v[8:9], s[4:5], v10, s42, v[0:1]
	v_ashrrev_i32_e32 v9, 3, v120
	v_mad_u64_u32 v[14:15], s[4:5], v9, s42, v[0:1]
	s_waitcnt vmcnt(11)
	ds_write_b128 v8, v[106:109]
	v_ashrrev_i32_e32 v8, 3, v122
	s_waitcnt vmcnt(10)
	ds_write_b128 v14, v[110:113]
	v_mad_u64_u32 v[14:15], s[4:5], v8, s42, v[0:1]
	s_waitcnt vmcnt(9)
	ds_write_b128 v14, v[114:117]
	s_and_saveexec_b64 s[4:5], vcc
	s_cbranch_execz .LBB0_1387
	s_mul_i32 s8, s7, 0x1d1
	v_add_u32_e32 v14, s8, v2
	v_readlane_b32 s68, v247, 33
	v_ashrrev_i32_e32 v15, 31, v14
	v_readlane_b32 s69, v247, 34
	v_lshl_add_u32 v13, v2, 2, v121
	v_readlane_b32 s70, v247, 35
	v_lshl_add_u64 v[14:15], v[14:15], 2, s[68:69]
	v_readlane_b32 s71, v247, 36
	v_readlane_b32 s72, v247, 37
	v_readlane_b32 s73, v247, 38
	v_readlane_b32 s74, v247, 39
	v_readlane_b32 s75, v247, 40
	v_readlane_b32 s76, v247, 41
	v_readlane_b32 s77, v247, 42
	v_readlane_b32 s78, v247, 43
	v_readlane_b32 s79, v247, 44
	v_readlane_b32 s80, v247, 45
	v_readlane_b32 s81, v247, 46
	v_readlane_b32 s82, v247, 47
	v_readlane_b32 s83, v247, 48
	s_waitcnt vmcnt(0)
	v_mul_f32_e32 v0, 0x3fb8aa3b, v214
	ds_write_b32 v13, v0
